# ring4+R4 + Q fragments resident in v[64:79] for the whole KV loop (no per-step Q LDS re-reads)
# speedup vs baseline: 1.0170x; 1.0170x over previous
.LBB0_397:
	s_and_b32 s45, s0, 15
	s_ashr_i32 s37, s36, 31
	s_mul_i32 s3, s36, 0x1800
	s_mul_hi_i32 s1, s36, 0x1800
	s_add_u32 s3, s78, s3
	v_readlane_b32 s2, v252, 50
	s_addc_u32 s1, s2, s1
	s_lshl_b32 s5, s45, 7
	s_add_u32 s30, s3, s5
	s_addc_u32 s31, s1, 0
	v_readlane_b32 s2, v250, 19
	v_readlane_b32 s3, v250, 20
	s_add_u32 s28, s2, s5
	v_mov_b32_e32 v6, v168
	s_addc_u32 s29, s3, 0
	s_lshl_b32 s0, s0, 7
	s_and_b32 s0, s0, 0x700
	v_ashrrev_i32_e32 v0, 6, v6
	v_and_b32_e32 v62, 63, v6
	v_and_b32_e32 v1, 0x3fffffc0, v6
	v_and_b32_e32 v200, 31, v6
	v_lshl_add_u32 v175, v1, 2, v192
	v_lshl_add_u32 v1, v0, 12, v192
	v_lshlrev_b32_e32 v7, 4, v62
	v_lshlrev_b32_e32 v174, 5, v0
	s_add_u32 s39, s73, s0
	v_bfe_u32 v201, v6, 5, 1
	v_add_u32_e32 v204, v1, v7
	v_or_b32_e32 v2, v174, v200
	v_mov_b64_e32 v[0:1], s[30:31]
	s_movk_i32 s0, 0x1800
	v_mad_i64_i32 v[0:1], s[0:1], v2, s0, v[0:1]
	v_lshlrev_b32_e32 v176, 4, v201
	v_mov_b32_e32 v177, v171
	v_lshl_add_u64 v[4:5], v[0:1], 0, v[176:177]
	global_load_dwordx4 v[0:3], v[4:5], off
	v_lshlrev_b32_e32 v12, 3, v6
	s_movk_i32 s1, 0xe0
	s_mov_b32 s0, 0x7ffffc
	s_addc_u32 s42, s63, 0
	s_cmp_lg_u32 0x100, -1
	s_mul_i32 s44, s38, 0x1800
	s_mul_hi_i32 s43, s38, 0x1800
	v_and_b32_e32 v8, 0x70, v6
	v_lshlrev_b32_e32 v72, 7, v200
	v_and_b32_e32 v73, 0x70, v12
	v_or_b32_e32 v64, 32, v176
	v_bitop3_b32 v64, v64, v72, v73 bitop3:0xde
	v_add_u32_e32 v209, 0x100, v64
	s_mov_b32 s5, s4
	s_mov_b32 s10, s4
	s_mov_b32 s11, s4
	s_mov_b32 s12, s4
	s_mov_b32 s13, s4
	s_mov_b32 s14, s4
	s_mov_b32 s15, s4
	s_mov_b32 s16, s4
	s_mov_b32 s17, s4
	s_mov_b32 s18, s4
	s_mov_b32 s19, s4
	v_mov_b32_e32 v61, v171
	v_cmp_gt_u32_e64 s[40:41], 32, v62
	s_mov_b32 s50, 4
	s_movk_i32 s51, 0xc0
	v_lshl_add_u32 v177, v200, 2, v175
	v_mov_b32_e32 v178, 0
	s_waitcnt vmcnt(0)
	ds_write_b128 v204, v[0:3] offset:51200
	global_load_dwordx4 v[0:3], v[4:5], off offset:32
	s_waitcnt vmcnt(0)
	ds_write_b128 v204, v[0:3] offset:52224
	global_load_dwordx4 v[0:3], v[4:5], off offset:64
	s_waitcnt vmcnt(0)
	ds_write_b128 v204, v[0:3] offset:53248
	global_load_dwordx4 v[0:3], v[4:5], off offset:96
	v_and_b32_e32 v5, 24, v12
	s_waitcnt vmcnt(0)
	ds_write_b128 v204, v[0:3] offset:54272
	v_ashrrev_i32_e32 v0, 4, v6
	v_lshlrev_b32_e32 v4, 5, v0
	v_lshrrev_b32_e32 v2, 5, v6
	v_bfe_u32 v3, v12, 5, 2
	v_and_or_b32 v4, v4, s1, v5
	v_and_or_b32 v2, v2, s0, v3
	v_lshlrev_b32_e32 v4, 1, v4
	v_lshl_or_b32 v13, v2, 9, v4
	v_add_u32_e32 v2, 32, v0
	v_lshrrev_b32_e32 v2, 1, v2
	v_and_or_b32 v2, v2, s0, v3
	s_movk_i32 s0, 0xc00
	v_and_b32_e32 v1, 0x78, v12
	v_mul_lo_u32 v0, v0, s0
	v_lshl_or_b32 v14, v2, 9, v4
	v_ashrrev_i32_e32 v2, 3, v6
	v_or_b32_e32 v0, v0, v1
	v_and_b32_e32 v3, 56, v12
	v_lshlrev_b32_e32 v170, 1, v0
	v_mul_lo_u32 v0, v2, s0
	v_or_b32_e32 v0, v0, v3
	s_cselect_b32 s0, 0x100, 0
	s_add_u32 s6, s39, s44
	v_lshlrev_b32_e32 v4, 7, v2
	v_lshlrev_b32_e32 v5, 1, v3
	v_lshlrev_b32_e32 v60, 1, v0
	v_lshlrev_b32_e32 v0, 3, v62
	v_and_b32_e32 v1, 0xc0, v7
	v_lshlrev_b32_e32 v2, 1, v6
	s_addc_u32 s7, s42, s43
	v_bitop3_b32 v15, v5, v4, v8 bitop3:0xde
	v_and_or_b32 v1, v0, 24, v1
	v_and_b32_e32 v2, 32, v2
	v_and_b32_e32 v0, 0x100, v0
	v_lshl_add_u64 v[4:5], s[6:7], 0, v[170:171]
	v_or3_b32 v63, v1, v2, v0
	s_add_u32 s8, s28, s44
	global_load_dwordx4 v[0:3], v170, s[6:7]
	v_add_co_u32_e32 v4, vcc, s33, v4
	s_addc_u32 s9, s29, s43
	s_nop 0
	v_addc_co_u32_e32 v5, vcc, 0, v5, vcc
	global_load_dwordx4 v[4:7], v[4:5], off
	v_add_u32_e32 v205, 0x100, v13
	global_load_dwordx4 v[8:11], v60, s[8:9]
	s_waitcnt vmcnt(0)
	v_add_u32_e32 v206, 0x100, v14
	v_add_u32_e32 v207, 0x100, v15
	s_mov_b32 s6, s4
	s_mov_b32 s7, s4
	s_mov_b32 s8, s4
	s_mov_b32 s9, s4
	s_add_i32 s1, s38, 64
	v_add_u32_e32 v203, s0, v63
	v_lshl_add_u64 v[180:181], s[28:29], 0, v[60:61]
	s_waitcnt vmcnt(2)
	ds_write_b128 v205, v[0:3]
	v_bitop3_b32 v0, v176, v72, v73 bitop3:0xde
	v_add_u32_e32 v208, 0x100, v0
	s_waitcnt vmcnt(1)
	ds_write_b128 v206, v[4:7]
	s_waitcnt vmcnt(0)
	ds_write_b128 v207, v[8:11] offset:32768
	s_waitcnt lgkmcnt(0)
	s_barrier
	ds_read_b128 v[56:59], v204 offset:52224
	ds_read_b128 v[52:55], v204 offset:53248
	ds_read_b128 v[48:51], v204 offset:54272
	ds_read_b128 v[16:19], v208 offset:36864
	ds_read_b128 v[20:23], v208 offset:32768
	ds_read_b128 v[24:27], v204 offset:51200
	s_waitcnt lgkmcnt(0)
	v_mfma_f32_32x32x16_bf16 v[32:47], v[20:23], v[24:27], 0
	ds_read_b128 v[64:67], v209 offset:36864
	ds_read_b128 v[68:71], v209 offset:32768
	v_mov_b64_e32 v[0:1], s[4:5]
	v_mov_b64_e32 v[2:3], s[6:7]
	v_mov_b64_e32 v[4:5], s[8:9]
	v_mov_b64_e32 v[6:7], s[10:11]
	v_mov_b64_e32 v[8:9], s[12:13]
	v_mov_b64_e32 v[10:11], s[14:15]
	v_mfma_f32_32x32x16_bf16 v[16:31], v[16:19], v[24:27], 0
	v_mov_b64_e32 v[12:13], s[16:17]
	v_mov_b64_e32 v[14:15], s[18:19]
	s_add_i32 s12, s44, 0x60000
	s_mul_hi_i32 s5, s1, 0x1800
	s_add_u32 s6, s39, s12
	s_addc_u32 s7, s42, s5
	s_add_u32 s8, s28, s12
	s_waitcnt lgkmcnt(0)
	v_mfma_f32_32x32x16_bf16 v[32:47], v[68:71], v[56:59], v[32:47]
	s_addc_u32 s9, s29, s5
	s_add_i32 s1, s38, 0x80
	s_add_i32 s47, s44, 0xc0000
	s_mul_hi_i32 s46, s1, 0x1800
	v_mfma_f32_32x32x16_bf16 v[16:31], v[64:67], v[56:59], v[16:31]
	v_or_b32_e32 v56, 64, v176
	v_bitop3_b32 v56, v56, v72, v73 bitop3:0xde
	v_add_u32_e32 v210, 0x100, v56
	ds_read_b128 v[56:59], v210 offset:36864
	ds_read_b128 v[64:67], v210 offset:32768
	s_waitcnt lgkmcnt(0)
	v_mfma_f32_32x32x16_bf16 v[32:47], v[64:67], v[52:55], v[32:47]
	v_mfma_f32_32x32x16_bf16 v[16:31], v[56:59], v[52:55], v[16:31]
	v_or_b32_e32 v52, 0x60, v176
	v_bitop3_b32 v52, v52, v72, v73 bitop3:0xde
	v_add_u32_e32 v211, 0x100, v52
	ds_read_b128 v[52:55], v211 offset:36864
	ds_read_b128 v[56:59], v211 offset:32768
	s_waitcnt lgkmcnt(0)
	v_mfma_f32_32x32x16_bf16 v[32:47], v[56:59], v[48:51], v[32:47]
	v_mfma_f32_32x32x16_bf16 v[16:31], v[52:55], v[48:51], v[16:31]
	s_nop 10
	v_max_f32_e32 v48, v33, v33
	v_max_f32_e32 v49, v32, v32
	v_max_f32_e32 v48, v49, v48
	v_max3_f32 v48, v48, v34, v35
	v_max3_f32 v48, v48, v36, v37
	v_max3_f32 v48, v48, v38, v39
	v_max3_f32 v48, v48, v40, v41
	v_max3_f32 v48, v48, v42, v43
	v_max3_f32 v48, v48, v44, v45
	v_max3_f32 v48, v48, v46, v47
	v_max3_f32 v48, v48, v16, v17
	v_max3_f32 v48, v48, v18, v19
	v_max3_f32 v48, v48, v20, v21
	v_max3_f32 v48, v48, v22, v23
	v_max3_f32 v48, v48, v24, v25
	v_max3_f32 v48, v48, v26, v27
	v_max3_f32 v48, v48, v28, v29
	v_max3_f32 v48, v48, v30, v31
	v_mov_b32_e32 v49, v48
	s_nop 1
	v_permlane32_swap_b32_e32 v48, v49
	v_max_f32_e32 v49, v49, v49
	v_max_f32_e32 v48, v48, v48
	v_max_f32_e32 v48, v48, v49
	v_sub_f32_e32 v36, v36, v48
	v_sub_f32_e32 v37, v37, v48
	v_exp_f32_e32 v53, v36
	v_exp_f32_e32 v54, v37
	v_lshl_add_u64 v[36:37], s[6:7], 0, v[170:171]
	v_add_co_u32_e32 v36, vcc, s33, v36
	v_sub_f32_e32 v32, v32, v48
	v_sub_f32_e32 v33, v33, v48
	v_sub_f32_e32 v34, v34, v48
	v_sub_f32_e32 v35, v35, v48
	v_sub_f32_e32 v38, v38, v48
	v_sub_f32_e32 v39, v39, v48
	v_sub_f32_e32 v40, v40, v48
	v_sub_f32_e32 v41, v41, v48
	v_sub_f32_e32 v42, v42, v48
	v_sub_f32_e32 v43, v43, v48
	v_sub_f32_e32 v44, v44, v48
	v_sub_f32_e32 v45, v45, v48
	v_sub_f32_e32 v46, v46, v48
	v_sub_f32_e32 v47, v47, v48
	v_addc_co_u32_e32 v37, vcc, 0, v37, vcc
	v_exp_f32_e32 v49, v32
	v_exp_f32_e32 v50, v33
	v_exp_f32_e32 v51, v34
	v_exp_f32_e32 v52, v35
	v_exp_f32_e32 v55, v38
	v_exp_f32_e32 v56, v39
	v_exp_f32_e32 v57, v40
	v_exp_f32_e32 v58, v41
	v_exp_f32_e32 v59, v42
	v_exp_f32_e32 v64, v43
	v_exp_f32_e32 v65, v44
	v_exp_f32_e32 v66, v45
	v_exp_f32_e32 v46, v46
	v_exp_f32_e32 v47, v47
	v_cvt_pk_bf16_f32 v144, v49, v50
	v_cvt_pk_bf16_f32 v145, v51, v52
	v_cvt_pk_bf16_f32 v146, v53, v54
	v_cvt_pk_bf16_f32 v147, v55, v56
	v_cvt_pk_bf16_f32 v140, v57, v58
	v_cvt_pk_bf16_f32 v141, v59, v64
	v_cvt_pk_bf16_f32 v142, v65, v66
	v_cvt_pk_bf16_f32 v143, v46, v47
	global_load_dwordx4 v[32:35], v170, s[6:7]
	s_nop 0
	global_load_dwordx4 v[36:39], v[36:37], off
	s_nop 0
	global_load_dwordx4 v[40:43], v60, s[8:9]
	s_add_u32 s6, s28, s47
	s_addc_u32 s7, s29, s46
	global_load_dwordx4 v[128:131], v60, s[6:7]
	s_add_u32 s6, s39, s47
	s_addc_u32 s7, s42, s46
	v_lshl_add_u64 v[44:45], s[6:7], 0, v[170:171]
	v_add_co_u32_e32 v44, vcc, s33, v44
	v_add_f32_e32 v212, 0, v48
	s_nop 0
	v_addc_co_u32_e32 v45, vcc, 0, v45, vcc
	global_load_dwordx4 v[136:139], v[44:45], off
	global_load_dwordx4 v[132:135], v170, s[6:7]
	s_waitcnt vmcnt(3)
	s_waitcnt vmcnt(5)
	ds_write_b128 v205, v[32:35] offset:16384
	s_waitcnt vmcnt(4)
	ds_write_b128 v206, v[36:39] offset:16384
	s_waitcnt vmcnt(3)
	ds_write_b128 v207, v[40:43] offset:40960
	v_add_f32_e32 v32, 0, v49
	v_add_f32_e32 v32, v50, v32
	v_add_f32_e32 v32, v51, v32
	v_add_f32_e32 v32, v52, v32
	v_add_f32_e32 v32, v53, v32
	v_add_f32_e32 v32, v54, v32
	v_add_f32_e32 v32, v55, v32
	v_add_f32_e32 v32, v56, v32
	v_add_f32_e32 v32, v57, v32
	v_add_f32_e32 v32, v58, v32
	v_add_f32_e32 v32, v59, v32
	v_add_f32_e32 v32, v64, v32
	v_add_f32_e32 v32, v65, v32
	v_add_f32_e32 v32, v66, v32
	v_add_f32_e32 v32, v46, v32
	s_addk_i32 s0, 0x4000
	v_xor_b32_e32 v96, 0x80000000, v212
	v_add_f32_e32 v164, v47, v32
	v_sub_f32_e32 v95, v31, v48
	v_sub_f32_e32 v94, v30, v48
	v_sub_f32_e32 v93, v29, v48
	v_sub_f32_e32 v92, v28, v48
	v_sub_f32_e32 v91, v27, v48
	v_sub_f32_e32 v90, v26, v48
	v_sub_f32_e32 v89, v25, v48
	v_sub_f32_e32 v88, v24, v48
	v_sub_f32_e32 v87, v23, v48
	v_sub_f32_e32 v86, v22, v48
	v_sub_f32_e32 v85, v21, v48
	v_sub_f32_e32 v84, v20, v48
	v_sub_f32_e32 v83, v19, v48
	v_sub_f32_e32 v82, v18, v48
	v_sub_f32_e32 v81, v17, v48
	v_sub_f32_e32 v80, v16, v48
	v_add_u32_e32 v202, s0, v63
	v_mov_b64_e32 v[62:63], v[14:15]
	v_mov_b64_e32 v[46:47], v[14:15]
	v_mov_b64_e32 v[30:31], v[14:15]
	s_mov_b64 s[8:9], 0
	v_mov_b64_e32 v[60:61], v[12:13]
	v_mov_b64_e32 v[58:59], v[10:11]
	v_mov_b64_e32 v[56:57], v[8:9]
	v_mov_b64_e32 v[54:55], v[6:7]
	v_mov_b64_e32 v[52:53], v[4:5]
	v_mov_b64_e32 v[50:51], v[2:3]
	v_mov_b64_e32 v[48:49], v[0:1]
	v_mov_b64_e32 v[44:45], v[12:13]
	v_mov_b64_e32 v[42:43], v[10:11]
	v_mov_b64_e32 v[40:41], v[8:9]
	v_mov_b64_e32 v[38:39], v[6:7]
	v_mov_b64_e32 v[36:37], v[4:5]
	v_mov_b64_e32 v[34:35], v[2:3]
	v_mov_b64_e32 v[32:33], v[0:1]
	v_mov_b64_e32 v[28:29], v[12:13]
	v_mov_b64_e32 v[26:27], v[10:11]
	v_mov_b64_e32 v[24:25], v[8:9]
	v_mov_b64_e32 v[22:23], v[6:7]
	v_mov_b64_e32 v[20:21], v[4:5]
	v_mov_b64_e32 v[18:19], v[2:3]
	v_mov_b64_e32 v[16:17], v[0:1]
	v_mov_b32_e32 v97, v96
	v_mov_b32_e32 v98, v96
	v_mov_b32_e32 v99, v96
	v_mov_b32_e32 v100, v96
	v_mov_b32_e32 v101, v96
	v_mov_b32_e32 v102, v96
	v_mov_b32_e32 v103, v96
	v_mov_b32_e32 v104, v96
	v_mov_b32_e32 v105, v96
	v_mov_b32_e32 v106, v96
	v_mov_b32_e32 v107, v96
	v_mov_b32_e32 v108, v96
	v_mov_b32_e32 v109, v96
	v_mov_b32_e32 v110, v96
	v_mov_b32_e32 v111, v96
	s_waitcnt lgkmcnt(0)
	s_barrier
	s_mov_b32 s100, 0x14800
	s_mov_b32 s101, 0x18010
	v_add_u32_e32 v205, s100, v205
	v_add_u32_e32 v206, s100, v206
	v_add_u32_e32 v207, s101, v207
	ds_read_b128 v[64:67], v204 offset:51200
	ds_read_b128 v[68:71], v204 offset:52224
	ds_read_b128 v[72:75], v204 offset:53248
	ds_read_b128 v[76:79], v204 offset:54272
	s_waitcnt lgkmcnt(0)
.LBB0_398:
	ds_read_b128 v[222:225], v208 offset:40960
	ds_read_b128 v[226:229], v208 offset:45056
	v_exp_f32_e32 v148, v80
	v_exp_f32_e32 v149, v81
	s_waitcnt lgkmcnt(1)
	v_mfma_f32_32x32x16_bf16 v[112:127], v[222:225], v[64:67], v[96:111]
	ds_read_b128 v[230:233], v209 offset:40960
	ds_read_b128 v[182:185], v209 offset:45056
	ds_read_b128 v[150:153], v210 offset:40960
	v_exp_f32_e32 v154, v84
	v_exp_f32_e32 v155, v85
	v_exp_f32_e32 v158, v86
	v_exp_f32_e32 v159, v87
	v_exp_f32_e32 v156, v90
	v_exp_f32_e32 v157, v91
	s_waitcnt lgkmcnt(2)
	v_mfma_f32_32x32x16_bf16 v[112:127], v[230:233], v[68:71], v[112:127]
	ds_read_b128 v[234:237], v210 offset:45056
	ds_read_b128 v[218:221], v211 offset:45056
	ds_read_b128 v[160:163], v211 offset:40960
	v_exp_f32_e32 v166, v94
	v_exp_f32_e32 v167, v95
	s_waitcnt lgkmcnt(3)
	v_mfma_f32_32x32x16_bf16 v[112:127], v[150:153], v[72:75], v[112:127]
	v_exp_f32_e32 v152, v82
	v_exp_f32_e32 v153, v83
	v_exp_f32_e32 v150, v88
	v_exp_f32_e32 v151, v89
	s_waitcnt lgkmcnt(0)
	v_mfma_f32_32x32x16_bf16 v[112:127], v[160:163], v[76:79], v[112:127]
	v_exp_f32_e32 v162, v92
	v_exp_f32_e32 v163, v93
	v_mfma_f32_32x32x16_bf16 v[80:95], v[226:229], v[64:67], v[96:111]
	v_add_f32_e32 v238, v164, v148
	v_add_f32_e32 v238, v149, v238
	v_add_f32_e32 v238, v152, v238
	v_add_f32_e32 v238, v153, v238
	v_add_f32_e32 v238, v154, v238
	v_add_f32_e32 v238, v155, v238
	v_add_f32_e32 v238, v158, v238
	v_mfma_f32_32x32x16_bf16 v[80:95], v[182:185], v[68:71], v[80:95]
	v_add_f32_e32 v238, v159, v238
	v_add_f32_e32 v238, v150, v238
	v_add_f32_e32 v238, v151, v238
	v_add_f32_e32 v238, v156, v238
	v_add_f32_e32 v238, v157, v238
	v_add_f32_e32 v238, v162, v238
	v_add_f32_e32 v238, v163, v238
	v_mfma_f32_32x32x16_bf16 v[80:95], v[234:237], v[72:75], v[80:95]
	v_add_f32_e32 v239, v166, v238
	v_add_f32_e32 v239, v167, v239
	v_mov_b32_e32 v240, v239
	s_nop 1
	v_permlane32_swap_b32_e32 v239, v240
	v_add_f32_e32 v164, v239, v240
	v_cmp_ge_f32_e32 vcc, s99, v164
	v_mfma_f32_32x32x16_bf16 v[80:95], v[218:221], v[76:79], v[80:95]
	s_cmp_eq_u64 vcc, exec
	s_cbranch_scc0 .LBB0_405
.LBB0_400:
	v_cvt_pk_bf16_f32 v182, v148, v149
	v_cvt_pk_bf16_f32 v183, v152, v153
	v_cvt_pk_bf16_f32 v184, v154, v155
	v_cvt_pk_bf16_f32 v185, v158, v159
	v_cvt_pk_bf16_f32 v160, v150, v151
	v_cvt_pk_bf16_f32 v161, v156, v157
	v_cvt_pk_bf16_f32 v162, v162, v163
	v_cvt_pk_bf16_f32 v163, v166, v167
	s_waitcnt vmcnt(0)
	ds_write_b128 v205, v[132:135]
	ds_write_b128 v206, v[136:139]
	ds_write_b128 v207, v[128:131] offset:32768
	s_cmpk_lt_u32 s51, 0x100
	s_cselect_b32 s0, s38, s34
	s_add_i32 s3, s0, s51
	s_mul_i32 s0, s3, 0x1800
	s_mul_hi_i32 s1, s3, 0x1800
	s_add_u32 s0, s39, s0
	s_addc_u32 s1, s42, s1
	v_lshl_add_u64 v[148:149], s[0:1], 0, v[170:171]
	v_add_co_u32_e32 v152, vcc, s33, v148
	v_mad_i64_i32 v[156:157], s[0:1], s3, v195, v[180:181]
	s_nop 0
	v_addc_co_u32_e32 v153, vcc, 0, v149, vcc
	global_load_dwordx4 v[148:151], v[148:149], off
	s_nop 0
	global_load_dwordx4 v[152:155], v[152:153], off
	s_nop 0
	global_load_dwordx4 v[156:159], v[156:157], off
	ds_read_b64_tr_b16 v[186:187], v203 offset:0
	ds_read_b64_tr_b16 v[188:189], v203 offset:0x800
	ds_read_b64_tr_b16 v[214:215], v203 offset:0x200
	ds_read_b64_tr_b16 v[216:217], v203 offset:0xa00
	ds_read_b64_tr_b16 v[218:219], v203 offset:0x400
	ds_read_b64_tr_b16 v[220:221], v203 offset:0xc00
	ds_read_b64_tr_b16 v[222:223], v203 offset:0x600
	ds_read_b64_tr_b16 v[224:225], v203 offset:0xe00
	ds_read_b64_tr_b16 v[226:227], v203 offset:0x1000
	ds_read_b64_tr_b16 v[228:229], v203 offset:0x1800
	ds_read_b64_tr_b16 v[230:231], v203 offset:0x1200
	ds_read_b64_tr_b16 v[232:233], v203 offset:0x1a00
	ds_read_b64_tr_b16 v[234:235], v203 offset:0x1400
	ds_read_b64_tr_b16 v[236:237], v203 offset:0x1c00
	ds_read_b64_tr_b16 v[238:239], v203 offset:0x1600
	ds_read_b64_tr_b16 v[240:241], v203 offset:0x1e00
	s_nop 0
	s_waitcnt lgkmcnt(8)
	v_exp_f32_e32 v112, v112
	v_mfma_f32_32x32x16_bf16 v[0:15], v[144:147], v[186:189], v[0:15]
	v_exp_f32_e32 v113, v113
	v_exp_f32_e32 v114, v114
	v_exp_f32_e32 v115, v115
	v_exp_f32_e32 v116, v116
	v_exp_f32_e32 v117, v117
	v_exp_f32_e32 v118, v118
	v_exp_f32_e32 v119, v119
	v_mfma_f32_32x32x16_bf16 v[48:63], v[144:147], v[214:217], v[48:63]
	v_exp_f32_e32 v120, v120
	v_exp_f32_e32 v121, v121
	v_exp_f32_e32 v122, v122
	v_exp_f32_e32 v123, v123
	v_exp_f32_e32 v124, v124
	v_exp_f32_e32 v125, v125
	v_exp_f32_e32 v126, v126
	v_mfma_f32_32x32x16_bf16 v[32:47], v[144:147], v[218:221], v[32:47]
	v_exp_f32_e32 v127, v127
	v_mfma_f32_32x32x16_bf16 v[16:31], v[144:147], v[222:225], v[16:31]
	ds_read_b64_tr_b16 v[144:145], v203 offset:0x2000
	ds_read_b64_tr_b16 v[146:147], v203 offset:0x2800
	ds_read_b64_tr_b16 v[186:187], v203 offset:0x2200
	ds_read_b64_tr_b16 v[188:189], v203 offset:0x2a00
	ds_read_b64_tr_b16 v[214:215], v203 offset:0x2400
	ds_read_b64_tr_b16 v[216:217], v203 offset:0x2c00
	ds_read_b64_tr_b16 v[218:219], v203 offset:0x2600
	ds_read_b64_tr_b16 v[220:221], v203 offset:0x2e00
	s_waitcnt lgkmcnt(8)
	ds_read_b64_tr_b16 v[222:223], v203 offset:0x3000
	ds_read_b64_tr_b16 v[224:225], v203 offset:0x3800
	s_nop 0
	v_mfma_f32_32x32x16_bf16 v[0:15], v[140:143], v[226:229], v[0:15]
	ds_read_b64_tr_b16 v[226:227], v203 offset:0x3200
	ds_read_b64_tr_b16 v[228:229], v203 offset:0x3a00
	v_mfma_f32_32x32x16_bf16 v[48:63], v[140:143], v[230:233], v[48:63]
	ds_read_b64_tr_b16 v[230:231], v203 offset:0x3400
	ds_read_b64_tr_b16 v[232:233], v203 offset:0x3c00
	v_mfma_f32_32x32x16_bf16 v[32:47], v[140:143], v[234:237], v[32:47]
	ds_read_b64_tr_b16 v[234:235], v203 offset:0x3600
	ds_read_b64_tr_b16 v[236:237], v203 offset:0x3e00
	s_waitcnt lgkmcnt(8)
	s_nop 0
	s_waitcnt lgkmcnt(0)
	v_mfma_f32_32x32x16_bf16 v[16:31], v[140:143], v[238:241], v[16:31]
	v_add_f32_e32 v140, 0, v112
	v_add_f32_e32 v140, v113, v140
	v_add_f32_e32 v140, v114, v140
	v_add_f32_e32 v140, v115, v140
	v_add_f32_e32 v140, v116, v140
	v_add_f32_e32 v140, v117, v140
	v_add_f32_e32 v140, v118, v140
	v_mfma_f32_32x32x16_bf16 v[0:15], v[182:185], v[144:147], v[0:15]
	v_add_f32_e32 v140, v119, v140
	v_add_f32_e32 v140, v120, v140
	v_add_f32_e32 v140, v121, v140
	v_add_f32_e32 v140, v122, v140
	v_add_f32_e32 v140, v123, v140
	v_add_f32_e32 v140, v124, v140
	v_add_f32_e32 v140, v125, v140
	v_mfma_f32_32x32x16_bf16 v[48:63], v[182:185], v[186:189], v[48:63]
	v_add_f32_e32 v140, v126, v140
	v_add_f32_e32 v165, v127, v140
	v_cvt_pk_bf16_f32 v144, v112, v113
	v_cvt_pk_bf16_f32 v145, v114, v115
	v_cvt_pk_bf16_f32 v146, v116, v117
	v_cvt_pk_bf16_f32 v147, v118, v119
	v_cvt_pk_bf16_f32 v140, v120, v121
	v_mfma_f32_32x32x16_bf16 v[32:47], v[182:185], v[214:217], v[32:47]
	v_cvt_pk_bf16_f32 v141, v122, v123
	v_cvt_pk_bf16_f32 v142, v124, v125
	v_cvt_pk_bf16_f32 v143, v126, v127
	v_mfma_f32_32x32x16_bf16 v[16:31], v[182:185], v[218:221], v[16:31]
	s_waitcnt lgkmcnt(0)
	s_barrier
	v_mfma_f32_32x32x16_bf16 v[0:15], v[160:163], v[222:225], v[0:15]
	v_mfma_f32_32x32x16_bf16 v[48:63], v[160:163], v[226:229], v[48:63]
	v_mfma_f32_32x32x16_bf16 v[32:47], v[160:163], v[230:233], v[32:47]
	v_mfma_f32_32x32x16_bf16 v[16:31], v[160:163], v[234:237], v[16:31]
	v_add_u32_e32 v208, s101, v208
	v_add_u32_e32 v209, s101, v209
	v_add_u32_e32 v210, s101, v210
	v_add_u32_e32 v211, s101, v211
	ds_read_b128 v[160:163], v208 offset:32768
	ds_read_b128 v[222:225], v208 offset:36864
	v_exp_f32_e32 v166, v84
	v_exp_f32_e32 v167, v85
	s_waitcnt lgkmcnt(1)
	v_mfma_f32_32x32x16_bf16 v[112:127], v[160:163], v[64:67], v[96:111]
	ds_read_b128 v[160:163], v209 offset:32768
	ds_read_b128 v[226:229], v209 offset:36864
	ds_read_b128 v[238:241], v210 offset:36864
	ds_read_b128 v[182:185], v210 offset:32768
	ds_read_b128 v[242:245], v211 offset:36864
	ds_read_b128 v[188:191], v211 offset:32768
	v_exp_f32_e32 v186, v90
	v_exp_f32_e32 v187, v91
	s_andn2_b64 s[0:1], s[6:7], exec
	s_and_b64 s[6:7], s[8:9], exec
	s_or_b64 s[6:7], s[0:1], s[6:7]
	s_waitcnt lgkmcnt(5)
	v_mfma_f32_32x32x16_bf16 v[112:127], v[160:163], v[68:71], v[112:127]
	v_exp_f32_e32 v160, v80
	v_exp_f32_e32 v161, v81
	v_exp_f32_e32 v162, v82
	v_exp_f32_e32 v163, v83
	v_add_f32_e32 v80, v160, v165
	v_add_f32_e32 v80, v161, v80
	v_add_f32_e32 v165, v162, v80
	s_waitcnt lgkmcnt(2)
	v_mfma_f32_32x32x16_bf16 v[112:127], v[182:185], v[72:75], v[112:127]
	v_exp_f32_e32 v182, v86
	v_exp_f32_e32 v183, v87
	v_exp_f32_e32 v184, v88
	v_exp_f32_e32 v185, v89
	v_add_f32_e32 v165, v163, v165
	v_add_f32_e32 v165, v166, v165
	v_add_f32_e32 v165, v167, v165
	s_waitcnt lgkmcnt(0)
	v_mfma_f32_32x32x16_bf16 v[112:127], v[188:191], v[76:79], v[112:127]
	v_exp_f32_e32 v188, v92
	v_exp_f32_e32 v189, v93
	v_exp_f32_e32 v190, v94
	v_exp_f32_e32 v191, v95
	v_add_f32_e32 v165, v182, v165
	v_add_f32_e32 v165, v183, v165
	v_add_f32_e32 v165, v184, v165
	v_mfma_f32_32x32x16_bf16 v[80:95], v[222:225], v[64:67], v[96:111]
	v_add_f32_e32 v165, v185, v165
	v_add_f32_e32 v165, v186, v165
	v_add_f32_e32 v165, v187, v165
	v_add_f32_e32 v165, v188, v165
	v_add_f32_e32 v165, v189, v165
	v_add_f32_e32 v165, v190, v165
	v_add_f32_e32 v165, v191, v165
	v_mfma_f32_32x32x16_bf16 v[80:95], v[226:229], v[68:71], v[80:95]
	v_mov_b32_e32 v179, v165
	s_nop 1
	v_permlane32_swap_b32_e32 v165, v179
	v_add_f32_e64 v178, v164, v178
	v_add_f32_e64 v179, v165, v179
	v_cmp_ge_f32_e32 vcc, s99, v179
	s_cmp_eq_u64 vcc, exec
	v_mfma_f32_32x32x16_bf16 v[80:95], v[238:241], v[72:75], v[80:95]
	v_mfma_f32_32x32x16_bf16 v[80:95], v[242:245], v[76:79], v[80:95]
	s_cbranch_scc0 .LBB0_408

.LBB0_405:
	v_log_f32_e32 v64, v164
	v_cmp_lt_f32_e32 vcc, s99, v164
	v_and_b32_e32 v67, 0xffff0000, v144
	v_add_f32_e32 v64, -4.0, v64
	v_cndmask_b32_e32 v65, 0, v64, vcc
	v_exp_f32_e64 v66, -v65
	v_lshlrev_b32_e32 v64, 16, v144
	v_mul_f32_e32 v64, v66, v64
	v_mul_f32_e32 v67, v66, v67
	v_cvt_pk_bf16_f32 v144, v64, v67
	v_lshlrev_b32_e32 v64, 16, v145
	v_and_b32_e32 v67, 0xffff0000, v145
	v_mul_f32_e32 v64, v66, v64
	v_mul_f32_e32 v67, v66, v67
	v_cvt_pk_bf16_f32 v145, v64, v67
	v_lshlrev_b32_e32 v64, 16, v146
	v_and_b32_e32 v67, 0xffff0000, v146
	v_mul_f32_e32 v64, v66, v64
	v_mul_f32_e32 v67, v66, v67
	v_cvt_pk_bf16_f32 v146, v64, v67
	v_lshlrev_b32_e32 v64, 16, v147
	v_and_b32_e32 v67, 0xffff0000, v147
	v_mul_f32_e32 v64, v66, v64
	v_mul_f32_e32 v67, v66, v67
	v_cvt_pk_bf16_f32 v147, v64, v67
	v_lshlrev_b32_e32 v64, 16, v140
	v_and_b32_e32 v67, 0xffff0000, v140
	v_mul_f32_e32 v64, v66, v64
	v_mul_f32_e32 v67, v66, v67
	v_cvt_pk_bf16_f32 v140, v64, v67
	v_lshlrev_b32_e32 v64, 16, v141
	v_and_b32_e32 v67, 0xffff0000, v141
	v_mul_f32_e32 v64, v66, v64
	v_mul_f32_e32 v67, v66, v67
	v_cvt_pk_bf16_f32 v141, v64, v67
	v_lshlrev_b32_e32 v64, 16, v142
	v_and_b32_e32 v67, 0xffff0000, v142
	v_mul_f32_e32 v64, v66, v64
	v_mul_f32_e32 v67, v66, v67
	v_cvt_pk_bf16_f32 v142, v64, v67
	v_lshlrev_b32_e32 v64, 16, v143
	v_and_b32_e32 v67, 0xffff0000, v143
	v_mul_f32_e32 v64, v66, v64
	v_mul_f32_e32 v67, v66, v67
	v_cvt_pk_bf16_f32 v143, v64, v67
	s_and_saveexec_b64 s[10:11], s[40:41]
	ds_write_b32 v177, v66 offset:49280
	s_or_b64 exec, exec, s[10:11]
	v_add_f32_e32 v212, v212, v65
	v_sub_f32_e32 v127, v127, v65
	v_sub_f32_e32 v126, v126, v65
	v_sub_f32_e32 v125, v125, v65
	v_sub_f32_e32 v124, v124, v65
	v_sub_f32_e32 v123, v123, v65
	v_sub_f32_e32 v122, v122, v65
	v_sub_f32_e32 v121, v121, v65
	v_sub_f32_e32 v120, v120, v65
	v_sub_f32_e32 v119, v119, v65
	v_sub_f32_e32 v118, v118, v65
	v_sub_f32_e32 v117, v117, v65
	v_sub_f32_e32 v116, v116, v65
	v_sub_f32_e32 v115, v115, v65
	v_sub_f32_e32 v114, v114, v65
	v_sub_f32_e32 v113, v113, v65
	v_sub_f32_e32 v112, v112, v65
	v_sub_f32_e32 v95, v95, v65
	v_sub_f32_e32 v94, v94, v65
	v_sub_f32_e32 v93, v93, v65
	v_sub_f32_e32 v92, v92, v65
	v_sub_f32_e32 v91, v91, v65
	v_sub_f32_e32 v90, v90, v65
	v_sub_f32_e32 v89, v89, v65
	v_sub_f32_e32 v88, v88, v65
	v_sub_f32_e32 v87, v87, v65
	v_sub_f32_e32 v86, v86, v65
	v_sub_f32_e32 v85, v85, v65
	v_sub_f32_e32 v84, v84, v65
	v_sub_f32_e32 v83, v83, v65
	v_sub_f32_e32 v82, v82, v65
	v_sub_f32_e32 v81, v81, v65
	v_sub_f32_e32 v80, v80, v65
	v_add_f32_e32 v65, v178, v164
	v_mul_f32_e32 v178, v65, v66
	s_waitcnt lgkmcnt(0)
	v_add_u32_e32 v65, v175, v176
	v_pk_mul_f32 v[166:167], v[166:167], v[66:67] op_sel_hi:[1,0]
	v_pk_mul_f32 v[162:163], v[162:163], v[66:67] op_sel_hi:[1,0]
	v_pk_mul_f32 v[156:157], v[156:157], v[66:67] op_sel_hi:[1,0]
	v_pk_mul_f32 v[150:151], v[150:151], v[66:67] op_sel_hi:[1,0]
	v_pk_mul_f32 v[158:159], v[158:159], v[66:67] op_sel_hi:[1,0]
	v_pk_mul_f32 v[154:155], v[154:155], v[66:67] op_sel_hi:[1,0]
	v_pk_mul_f32 v[152:153], v[152:153], v[66:67] op_sel_hi:[1,0]
	v_pk_mul_f32 v[148:149], v[148:149], v[66:67] op_sel_hi:[1,0]
	ds_read_b128 v[66:69], v65 offset:49280
	ds_read_b128 v[70:73], v65 offset:49312
	ds_read_b128 v[74:77], v65 offset:49344
	ds_read_b128 v[96:99], v65 offset:49376
	s_mov_b32 s0, 0x71800000
	v_xor_b32_e32 v64, 0x80000000, v212
	v_cmp_ngt_f32_e32 vcc, s0, v164
	s_or_b64 s[8:9], s[8:9], vcc
	s_waitcnt lgkmcnt(0)
	v_pk_mul_f32 v[12:13], v[12:13], v[96:97]
	v_pk_mul_f32 v[8:9], v[8:9], v[74:75]
	v_pk_mul_f32 v[4:5], v[4:5], v[70:71]
	v_pk_mul_f32 v[14:15], v[14:15], v[98:99]
	v_pk_mul_f32 v[10:11], v[10:11], v[76:77]
	v_pk_mul_f32 v[6:7], v[6:7], v[72:73]
	v_pk_mul_f32 v[2:3], v[2:3], v[68:69]
	v_pk_mul_f32 v[0:1], v[0:1], v[66:67]
	v_pk_mul_f32 v[60:61], v[60:61], v[96:97]
	v_pk_mul_f32 v[56:57], v[56:57], v[74:75]
	v_pk_mul_f32 v[52:53], v[52:53], v[70:71]
	v_pk_mul_f32 v[62:63], v[62:63], v[98:99]
	v_pk_mul_f32 v[58:59], v[58:59], v[76:77]
	v_pk_mul_f32 v[54:55], v[54:55], v[72:73]
	v_pk_mul_f32 v[50:51], v[50:51], v[68:69]
	v_pk_mul_f32 v[48:49], v[48:49], v[66:67]
	v_pk_mul_f32 v[44:45], v[44:45], v[96:97]
	v_pk_mul_f32 v[40:41], v[40:41], v[74:75]
	v_pk_mul_f32 v[36:37], v[36:37], v[70:71]
	v_pk_mul_f32 v[46:47], v[46:47], v[98:99]
	v_pk_mul_f32 v[42:43], v[42:43], v[76:77]
	v_pk_mul_f32 v[38:39], v[38:39], v[72:73]
	v_pk_mul_f32 v[34:35], v[34:35], v[68:69]
	v_pk_mul_f32 v[32:33], v[32:33], v[66:67]
	v_pk_mul_f32 v[28:29], v[28:29], v[96:97]
	v_pk_mul_f32 v[24:25], v[24:25], v[74:75]
	v_pk_mul_f32 v[20:21], v[20:21], v[70:71]
	v_pk_mul_f32 v[30:31], v[30:31], v[98:99]
	v_pk_mul_f32 v[26:27], v[26:27], v[76:77]
	v_pk_mul_f32 v[22:23], v[22:23], v[72:73]
	v_pk_mul_f32 v[18:19], v[18:19], v[68:69]
	v_pk_mul_f32 v[16:17], v[16:17], v[66:67]
	v_mov_b32_e32 v65, v64
	v_mov_b32_e32 v66, v64
	v_mov_b32_e32 v67, v64
	v_mov_b32_e32 v68, v64
	v_mov_b32_e32 v69, v64
	v_mov_b32_e32 v70, v64
	v_mov_b32_e32 v71, v64
	v_mov_b32_e32 v72, v64
	v_mov_b32_e32 v73, v64
	v_mov_b32_e32 v74, v64
	v_mov_b32_e32 v75, v64
	v_mov_b32_e32 v76, v64
	v_mov_b32_e32 v77, v64
	v_mov_b32_e32 v78, v64
	v_mov_b32_e32 v79, v64
	v_mov_b32_e32 v164, 0
	v_mov_b32_e32 v111, v64
	v_mov_b32_e32 v110, v64
	v_mov_b32_e32 v109, v64
	v_mov_b32_e32 v108, v64
	v_mov_b32_e32 v107, v64
	v_mov_b32_e32 v106, v64
	v_mov_b32_e32 v105, v64
	v_mov_b32_e32 v104, v64
	v_mov_b32_e32 v103, v64
	v_mov_b32_e32 v102, v64
	v_mov_b32_e32 v101, v64
	v_mov_b32_e32 v100, v64
	v_mov_b32_e32 v99, v64
	v_mov_b32_e32 v98, v64
	v_mov_b32_e32 v97, v64
	v_mov_b32_e32 v96, v64
	ds_read_b128 v[64:67], v204 offset:51200
	ds_read_b128 v[68:71], v204 offset:52224
	ds_read_b128 v[72:75], v204 offset:53248
	ds_read_b128 v[76:79], v204 offset:54272
	s_waitcnt lgkmcnt(0)
	s_branch .LBB0_400
.LBB0_408:
	v_log_f32_e32 v64, v179
	v_cmp_lt_f32_e32 vcc, s99, v179
	v_and_b32_e32 v67, 0xffff0000, v144
	v_add_f32_e32 v64, -4.0, v64
	v_cndmask_b32_e32 v65, 0, v64, vcc
	v_exp_f32_e64 v66, -v65
	v_lshlrev_b32_e32 v64, 16, v144
	v_mul_f32_e32 v64, v66, v64
	v_mul_f32_e32 v67, v66, v67
	v_cvt_pk_bf16_f32 v144, v64, v67
	v_lshlrev_b32_e32 v64, 16, v145
	v_and_b32_e32 v67, 0xffff0000, v145
	v_mul_f32_e32 v64, v66, v64
	v_mul_f32_e32 v67, v66, v67
	v_cvt_pk_bf16_f32 v145, v64, v67
	v_lshlrev_b32_e32 v64, 16, v146
	v_and_b32_e32 v67, 0xffff0000, v146
	v_mul_f32_e32 v64, v66, v64
	v_mul_f32_e32 v67, v66, v67
	v_cvt_pk_bf16_f32 v146, v64, v67
	v_lshlrev_b32_e32 v64, 16, v147
	v_and_b32_e32 v67, 0xffff0000, v147
	v_mul_f32_e32 v64, v66, v64
	v_mul_f32_e32 v67, v66, v67
	v_cvt_pk_bf16_f32 v147, v64, v67
	v_lshlrev_b32_e32 v64, 16, v140
	v_and_b32_e32 v67, 0xffff0000, v140
	v_mul_f32_e32 v64, v66, v64
	v_mul_f32_e32 v67, v66, v67
	v_cvt_pk_bf16_f32 v140, v64, v67
	v_lshlrev_b32_e32 v64, 16, v141
	v_and_b32_e32 v67, 0xffff0000, v141
	v_mul_f32_e32 v64, v66, v64
	v_mul_f32_e32 v67, v66, v67
	v_cvt_pk_bf16_f32 v141, v64, v67
	v_lshlrev_b32_e32 v64, 16, v142
	v_and_b32_e32 v67, 0xffff0000, v142
	v_mul_f32_e32 v64, v66, v64
	v_mul_f32_e32 v67, v66, v67
	v_cvt_pk_bf16_f32 v142, v64, v67
	v_lshlrev_b32_e32 v64, 16, v143
	v_and_b32_e32 v67, 0xffff0000, v143
	v_mul_f32_e32 v64, v66, v64
	v_mul_f32_e32 v67, v66, v67
	v_cvt_pk_bf16_f32 v143, v64, v67
	s_and_saveexec_b64 s[10:11], s[40:41]
	ds_write_b32 v177, v66 offset:49280
	s_or_b64 exec, exec, s[10:11]
	v_add_f32_e32 v212, v212, v65
	v_sub_f32_e32 v127, v127, v65
	v_sub_f32_e32 v126, v126, v65
	v_sub_f32_e32 v125, v125, v65
	v_sub_f32_e32 v124, v124, v65
	v_sub_f32_e32 v123, v123, v65
	v_sub_f32_e32 v122, v122, v65
	v_sub_f32_e32 v121, v121, v65
	v_sub_f32_e32 v120, v120, v65
	v_sub_f32_e32 v119, v119, v65
	v_sub_f32_e32 v118, v118, v65
	v_sub_f32_e32 v117, v117, v65
	v_sub_f32_e32 v116, v116, v65
	v_sub_f32_e32 v115, v115, v65
	v_sub_f32_e32 v114, v114, v65
	v_sub_f32_e32 v113, v113, v65
	v_sub_f32_e32 v112, v112, v65
	v_sub_f32_e32 v95, v95, v65
	v_sub_f32_e32 v94, v94, v65
	v_sub_f32_e32 v93, v93, v65
	v_sub_f32_e32 v92, v92, v65
	v_sub_f32_e32 v91, v91, v65
	v_sub_f32_e32 v90, v90, v65
	v_sub_f32_e32 v89, v89, v65
	v_sub_f32_e32 v88, v88, v65
	v_sub_f32_e32 v87, v87, v65
	v_sub_f32_e32 v86, v86, v65
	v_sub_f32_e32 v85, v85, v65
	v_sub_f32_e32 v84, v84, v65
	v_sub_f32_e32 v83, v83, v65
	v_sub_f32_e32 v82, v82, v65
	v_sub_f32_e32 v81, v81, v65
	v_sub_f32_e32 v80, v80, v65
	v_add_f32_e32 v65, v178, v179
	v_mul_f32_e32 v178, v65, v66
	s_waitcnt lgkmcnt(0)
	v_add_u32_e32 v65, v175, v176
	v_pk_mul_f32 v[190:191], v[190:191], v[66:67] op_sel_hi:[1,0]
	v_pk_mul_f32 v[188:189], v[188:189], v[66:67] op_sel_hi:[1,0]
	v_pk_mul_f32 v[186:187], v[186:187], v[66:67] op_sel_hi:[1,0]
	v_pk_mul_f32 v[184:185], v[184:185], v[66:67] op_sel_hi:[1,0]
	v_pk_mul_f32 v[182:183], v[182:183], v[66:67] op_sel_hi:[1,0]
	v_pk_mul_f32 v[166:167], v[166:167], v[66:67] op_sel_hi:[1,0]
	v_pk_mul_f32 v[162:163], v[162:163], v[66:67] op_sel_hi:[1,0]
	v_pk_mul_f32 v[160:161], v[160:161], v[66:67] op_sel_hi:[1,0]
	ds_read_b128 v[66:69], v65 offset:49280
	ds_read_b128 v[70:73], v65 offset:49312
	ds_read_b128 v[74:77], v65 offset:49344
	ds_read_b128 v[96:99], v65 offset:49376
	s_mov_b32 s0, 0x71800000
	v_cmp_ngt_f32_e32 vcc, s0, v179
	s_or_b64 s[8:9], s[8:9], vcc
	v_xor_b32_e32 v64, 0x80000000, v212
	s_andn2_b64 s[0:1], s[6:7], exec
	s_and_b64 s[6:7], s[8:9], exec
	s_waitcnt lgkmcnt(0)
	v_pk_mul_f32 v[12:13], v[12:13], v[96:97]
	v_pk_mul_f32 v[8:9], v[8:9], v[74:75]
	v_pk_mul_f32 v[4:5], v[4:5], v[70:71]
	v_pk_mul_f32 v[14:15], v[14:15], v[98:99]
	v_pk_mul_f32 v[10:11], v[10:11], v[76:77]
	v_pk_mul_f32 v[6:7], v[6:7], v[72:73]
	v_pk_mul_f32 v[2:3], v[2:3], v[68:69]
	v_pk_mul_f32 v[0:1], v[0:1], v[66:67]
	v_pk_mul_f32 v[60:61], v[60:61], v[96:97]
	v_pk_mul_f32 v[56:57], v[56:57], v[74:75]
	v_pk_mul_f32 v[52:53], v[52:53], v[70:71]
	v_pk_mul_f32 v[62:63], v[62:63], v[98:99]
	v_pk_mul_f32 v[58:59], v[58:59], v[76:77]
	v_pk_mul_f32 v[54:55], v[54:55], v[72:73]
	v_pk_mul_f32 v[50:51], v[50:51], v[68:69]
	v_pk_mul_f32 v[48:49], v[48:49], v[66:67]
	v_pk_mul_f32 v[44:45], v[44:45], v[96:97]
	v_pk_mul_f32 v[40:41], v[40:41], v[74:75]
	v_pk_mul_f32 v[36:37], v[36:37], v[70:71]
	v_pk_mul_f32 v[46:47], v[46:47], v[98:99]
	v_pk_mul_f32 v[42:43], v[42:43], v[76:77]
	v_pk_mul_f32 v[38:39], v[38:39], v[72:73]
	v_pk_mul_f32 v[34:35], v[34:35], v[68:69]
	v_pk_mul_f32 v[32:33], v[32:33], v[66:67]
	v_pk_mul_f32 v[28:29], v[28:29], v[96:97]
	v_pk_mul_f32 v[24:25], v[24:25], v[74:75]
	v_pk_mul_f32 v[20:21], v[20:21], v[70:71]
	v_pk_mul_f32 v[30:31], v[30:31], v[98:99]
	v_pk_mul_f32 v[26:27], v[26:27], v[76:77]
	v_pk_mul_f32 v[22:23], v[22:23], v[72:73]
	v_pk_mul_f32 v[18:19], v[18:19], v[68:69]
	v_pk_mul_f32 v[16:17], v[16:17], v[66:67]
	v_mov_b32_e32 v65, v64
	v_mov_b32_e32 v66, v64
	v_mov_b32_e32 v67, v64
	v_mov_b32_e32 v68, v64
	v_mov_b32_e32 v69, v64
	v_mov_b32_e32 v70, v64
	v_mov_b32_e32 v71, v64
	v_mov_b32_e32 v72, v64
	v_mov_b32_e32 v73, v64
	v_mov_b32_e32 v74, v64
	v_mov_b32_e32 v75, v64
	v_mov_b32_e32 v76, v64
	v_mov_b32_e32 v77, v64
	v_mov_b32_e32 v78, v64
	v_mov_b32_e32 v79, v64
	v_mov_b32_e32 v179, 0
	s_or_b64 s[6:7], s[0:1], s[6:7]
	v_mov_b32_e32 v111, v64
	v_mov_b32_e32 v110, v64
	v_mov_b32_e32 v109, v64
	v_mov_b32_e32 v108, v64
	v_mov_b32_e32 v107, v64
	v_mov_b32_e32 v106, v64
	v_mov_b32_e32 v105, v64
	v_mov_b32_e32 v104, v64
	v_mov_b32_e32 v103, v64
	v_mov_b32_e32 v102, v64
	v_mov_b32_e32 v101, v64
	v_mov_b32_e32 v100, v64
	v_mov_b32_e32 v99, v64
	v_mov_b32_e32 v98, v64
	v_mov_b32_e32 v97, v64
	v_mov_b32_e32 v96, v64
	ds_read_b128 v[64:67], v204 offset:51200
	ds_read_b128 v[68:71], v204 offset:52224
	ds_read_b128 v[72:75], v204 offset:53248
	ds_read_b128 v[76:79], v204 offset:54272
	s_waitcnt lgkmcnt(0)
	s_branch .LBB0_401
